# GEMM MMA blocks: no-op s_setprio 0 / s_setprio 1 pairs between the two 16-MFMA groups removed
# baseline (speedup 1.0000x reference)
; #define PG8_STAGE(bufoff, gbase, voff) do { _Pragma("unroll") for (int _i = 0; _i < 2; ++_i) \
;         __builtin_amdgcn_global_load_lds((const unsigned*)((const char*)(gbase) + (voff)[_i]), (PG8_LAS unsigned*)(lds + (bufoff) + ldsw + _i * 8192), 16, 0, 0); } while (0)
; #define PG8_LDA(dst, b, h) do { _Pragma("unroll") for (int m = 0; m < 4; ++m) _Pragma("unroll") for (int k = 0; k < 2; ++k) dst[m][k] = *(const PG8_LAS bf16x8*)(lds + PG8_SA(b, h) + aoff + m * 2048 + k * 1024); } while (0)
; #define PG8_LDB(dst, b, h) do { _Pragma("unroll") for (int n = 0; n < 2; ++n) _Pragma("unroll") for (int k = 0; k < 2; ++k) dst[n][k] = *(const PG8_LAS bf16x8*)(lds + PG8_SB(b, h) + boff + n * 2048 + k * 1024); } while (0)
; #define PG8_MMA(ai, bj, At, Bt) do { __builtin_amdgcn_s_setprio(1); _Pragma("unroll") for (int m = 0; m < 4; ++m) _Pragma("unroll") for (int n = 0; n < 2; ++n) _Pragma("unroll") for (int k = 0; k < 2; ++k) \
;         acc[ai][bj][m][n] = __builtin_amdgcn_mfma_f32_16x16x32_bf16(Bt[n][k], At[m][k], acc[ai][bj][m][n], 0, 0, 0); __builtin_amdgcn_s_setprio(0); } while (0)
; #define PG8_WAIT_V(n) asm volatile("s_waitcnt vmcnt(" #n ")" ::: "memory")
; #define PG8_BAR __builtin_amdgcn_s_barrier()
; template <class Epi, class Sched, bool ALIGN_EPI = false, bool SP2 = false>
; __device__ __forceinline__ void gemm_phase(PG8_LAS unsigned char* lds, const Gemm g, const Sched& S, const Epi& E) {
;     ...
;         for (int t = 0; t < nt; t += 2) {
;             const bool last = (t == nt - 2);
;             const char* a1 = cA + (size_t)(t + 1) * kstepA;
;             const char* a2 = last ? nA : cA + (size_t)(t + 2) * kstepA; const char* b2 = last ? nB : cB + (size_t)(t + 2) * kstepB;
;             const char* a3 = a2 + kstepA; const char* b3 = b2 + kstepB;
;             if (last && has_next) S.a_ready(nxt);
;             if constexpr (SP2) {
;             PG8_LDB(B0, 0, 0); PG8_LDB(B1, 0, 1); PG8_SCHED; PG8_LDA(At, 0, 0); PG8_STAGE(PG8_SA(1, 1), a1 + hstepB, voffA);
;             PG8_WAIT_V(8); PG8_WAIT_L(0); PG8_BAR; PG8_MMA(0, 0, At, B0); PG8_MMA(0, 1, At, B1); PG8_BAR; PG8_SCHED;
;             PG8_LDA(At, 0, 1); PG8_STAGE(PG8_SB(0, 0), b2, voffB); PG8_STAGE(PG8_SB(0, 1), b2 + hstepB, voffB); PG8_STAGE(PG8_SA(0, 0), a2, voffA);
;             PG8_WAIT_V(8); PG8_WAIT_L(0); PG8_BAR; PG8_MMA(1, 0, At, B0); PG8_MMA(1, 1, At, B1); PG8_BAR; PG8_SCHED;
.LBB0_372:
	s_add_i32 s71, s71, 2
	s_add_u32 s12, s6, 0x1fc000
	s_addc_u32 s13, s7, 0
	s_and_b64 s[26:27], exec, s[26:27]
	s_cselect_b32 s26, s69, s12
	s_cselect_b32 s27, s59, s13
	s_add_u32 vcc_lo, s26, 0x200000
	s_addc_u32 vcc_hi, s27, 0
	s_add_i32 s12, 0, 0x10000
	v_add_u32_e32 v142, s12, v144
	s_add_i32 s73, 0, 0x14000
	ds_read_b128 v[148:151], v142
	ds_read_b128 v[152:155], v142 offset:1024
	ds_read_b128 v[156:159], v142 offset:2048
	ds_read_b128 v[160:163], v142 offset:3072
	v_add_u32_e32 v142, s73, v144
	ds_read_b128 v[164:167], v142
	ds_read_b128 v[168:171], v142 offset:1024
	ds_read_b128 v[172:175], v142 offset:2048
	ds_read_b128 v[176:179], v142 offset:3072
	v_lshl_add_u64 v[142:143], s[6:7], 0, v[138:139]
	s_add_i32 m0, s45, 0xc000
	ds_read_b128 v[180:183], v146
	ds_read_b128 v[184:187], v146 offset:1024
	ds_read_b128 v[188:191], v146 offset:2048
	ds_read_b128 v[192:195], v146 offset:3072
	ds_read_b128 v[196:199], v146 offset:4096
	ds_read_b128 v[200:203], v146 offset:5120
	ds_read_b128 v[204:207], v146 offset:6144
	ds_read_b128 v[222:225], v146 offset:7168
	global_load_lds_dwordx4 v[142:143], off
	v_lshl_add_u64 v[142:143], s[6:7], 0, v[140:141]
	s_add_i32 m0, s45, 0xe000
	s_nop 0
	global_load_lds_dwordx4 v[142:143], off
	s_waitcnt vmcnt(8)
	s_waitcnt lgkmcnt(0)
	s_barrier
	s_setprio 1
	s_waitcnt lgkmcnt(0)
	v_mfma_f32_16x16x32_bf16 v[126:129], v[148:151], v[180:183], v[126:129]
	v_mfma_f32_16x16x32_bf16 v[122:125], v[156:159], v[180:183], v[122:125]
	v_mfma_f32_16x16x32_bf16 v[114:117], v[148:151], v[188:191], v[114:117]
	v_mfma_f32_16x16x32_bf16 v[106:109], v[156:159], v[188:191], v[106:109]
	v_mfma_f32_16x16x32_bf16 v[98:101], v[148:151], v[196:199], v[98:101]
	v_mfma_f32_16x16x32_bf16 v[90:93], v[156:159], v[196:199], v[90:93]
	v_mfma_f32_16x16x32_bf16 v[82:85], v[148:151], v[204:207], v[82:85]
	v_mfma_f32_16x16x32_bf16 v[74:77], v[156:159], v[204:207], v[74:77]
	v_mfma_f32_16x16x32_bf16 v[126:129], v[152:155], v[184:187], v[126:129]
	v_mfma_f32_16x16x32_bf16 v[122:125], v[160:163], v[184:187], v[122:125]
	v_mfma_f32_16x16x32_bf16 v[114:117], v[152:155], v[192:195], v[114:117]
	v_mfma_f32_16x16x32_bf16 v[106:109], v[160:163], v[192:195], v[106:109]
	v_mfma_f32_16x16x32_bf16 v[98:101], v[152:155], v[200:203], v[98:101]
	v_mfma_f32_16x16x32_bf16 v[90:93], v[160:163], v[200:203], v[90:93]
	v_mfma_f32_16x16x32_bf16 v[82:85], v[152:155], v[222:225], v[82:85]
	v_mfma_f32_16x16x32_bf16 v[74:77], v[160:163], v[222:225], v[74:77]
	v_mfma_f32_16x16x32_bf16 v[118:121], v[164:167], v[180:183], v[118:121]
	v_mfma_f32_16x16x32_bf16 v[110:113], v[172:175], v[180:183], v[110:113]
	v_mfma_f32_16x16x32_bf16 v[102:105], v[164:167], v[188:191], v[102:105]
	v_mfma_f32_16x16x32_bf16 v[94:97], v[172:175], v[188:191], v[94:97]
	v_mfma_f32_16x16x32_bf16 v[86:89], v[164:167], v[196:199], v[86:89]
	v_mfma_f32_16x16x32_bf16 v[78:81], v[172:175], v[196:199], v[78:81]
	v_mfma_f32_16x16x32_bf16 v[70:73], v[164:167], v[204:207], v[70:73]
	v_mfma_f32_16x16x32_bf16 v[66:69], v[172:175], v[204:207], v[66:69]
	v_mfma_f32_16x16x32_bf16 v[118:121], v[168:171], v[184:187], v[118:121]
	v_mfma_f32_16x16x32_bf16 v[110:113], v[176:179], v[184:187], v[110:113]
	v_mfma_f32_16x16x32_bf16 v[102:105], v[168:171], v[192:195], v[102:105]
	v_mfma_f32_16x16x32_bf16 v[94:97], v[176:179], v[192:195], v[94:97]
	v_mfma_f32_16x16x32_bf16 v[86:89], v[168:171], v[200:203], v[86:89]
	v_mfma_f32_16x16x32_bf16 v[78:81], v[176:179], v[200:203], v[78:81]
	v_mfma_f32_16x16x32_bf16 v[70:73], v[168:171], v[222:225], v[70:73]
	v_mfma_f32_16x16x32_bf16 v[66:69], v[176:179], v[222:225], v[66:69]
	s_setprio 0
	s_barrier
	s_add_i32 s12, s12, s23
	v_lshl_add_u64 v[142:143], s[74:75], 0, v[134:135]
	s_mov_b32 m0, s12
	ds_read_b128 v[180:183], v146 offset:16384
	ds_read_b128 v[184:187], v146 offset:17408
	ds_read_b128 v[188:191], v146 offset:18432
	ds_read_b128 v[192:195], v146 offset:19456
	ds_read_b128 v[196:199], v146 offset:20480
	ds_read_b128 v[200:203], v146 offset:21504
	ds_read_b128 v[204:207], v146 offset:22528
	ds_read_b128 v[222:225], v146 offset:23552
	global_load_lds_dwordx4 v[142:143], off
	s_add_i32 m0, s12, 0x2000
	s_add_u32 s12, s74, 0x4000
	v_lshl_add_u64 v[142:143], s[74:75], 0, v[130:131]
	s_addc_u32 s13, s75, 0
	s_add_i32 s73, s73, s23
	global_load_lds_dwordx4 v[142:143], off
	v_lshl_add_u64 v[142:143], s[12:13], 0, v[134:135]
	s_mov_b32 m0, s73
	s_nop 0
	global_load_lds_dwordx4 v[142:143], off
	v_lshl_add_u64 v[142:143], s[12:13], 0, v[130:131]
	s_add_i32 m0, s73, 0x2000
	s_nop 0
	global_load_lds_dwordx4 v[142:143], off
	v_lshl_add_u64 v[142:143], s[26:27], 0, v[136:137]
	s_mov_b32 m0, s45
	s_nop 0
	global_load_lds_dwordx4 v[142:143], off
	v_lshl_add_u64 v[142:143], s[26:27], 0, v[132:133]
	s_mov_b32 m0, s49
	s_nop 0
	global_load_lds_dwordx4 v[142:143], off
	s_waitcnt vmcnt(8)
	s_waitcnt lgkmcnt(0)
	s_barrier
; #define PG8_STAGE(bufoff, gbase, voff) do { _Pragma("unroll") for (int _i = 0; _i < 2; ++_i) \
;         __builtin_amdgcn_global_load_lds((const unsigned*)((const char*)(gbase) + (voff)[_i]), (PG8_LAS unsigned*)(lds + (bufoff) + ldsw + _i * 8192), 16, 0, 0); } while (0)
; #define PG8_LDA(dst, b, h) do { _Pragma("unroll") for (int m = 0; m < 4; ++m) _Pragma("unroll") for (int k = 0; k < 2; ++k) dst[m][k] = *(const PG8_LAS bf16x8*)(lds + PG8_SA(b, h) + aoff + m * 2048 + k * 1024); } while (0)
; #define PG8_LDB(dst, b, h) do { _Pragma("unroll") for (int n = 0; n < 2; ++n) _Pragma("unroll") for (int k = 0; k < 2; ++k) dst[n][k] = *(const PG8_LAS bf16x8*)(lds + PG8_SB(b, h) + boff + n * 2048 + k * 1024); } while (0)
; #define PG8_MMA(ai, bj, At, Bt) do { __builtin_amdgcn_s_setprio(1); _Pragma("unroll") for (int m = 0; m < 4; ++m) _Pragma("unroll") for (int n = 0; n < 2; ++n) _Pragma("unroll") for (int k = 0; k < 2; ++k) \
;         acc[ai][bj][m][n] = __builtin_amdgcn_mfma_f32_16x16x32_bf16(Bt[n][k], At[m][k], acc[ai][bj][m][n], 0, 0, 0); __builtin_amdgcn_s_setprio(0); } while (0)
; #define PG8_WAIT_V(n) asm volatile("s_waitcnt vmcnt(" #n ")" ::: "memory")
; #define PG8_WAIT_L(n) asm volatile("s_waitcnt lgkmcnt(" #n ")" ::: "memory")
; #define PG8_BAR __builtin_amdgcn_s_barrier()
; #define PG8_SCHED __builtin_amdgcn_sched_barrier(0)
; template <class Epi, class Sched, bool ALIGN_EPI = false, bool SP2 = false>
; __device__ __forceinline__ void gemm_phase(PG8_LAS unsigned char* lds, const Gemm g, const Sched& S, const Epi& E) {
;     ...
;             PG8_WAIT_V(8); PG8_WAIT_L(0); PG8_BAR; PG8_MMA(1, 0, At, B0); PG8_MMA(1, 1, At, B1); PG8_BAR; PG8_SCHED;
;             PG8_LDB(B0, 1, 0); PG8_LDB(B1, 1, 1); PG8_SCHED; PG8_LDA(At, 1, 0); PG8_STAGE(PG8_SA(0, 1), a2 + hstepB, voffA);
;             PG8_WAIT_V(8); PG8_WAIT_L(0); PG8_BAR; PG8_MMA(0, 0, At, B0); PG8_MMA(0, 1, At, B1); PG8_BAR; PG8_SCHED;
	s_setprio 1
	s_waitcnt lgkmcnt(0)
	v_mfma_f32_16x16x32_bf16 v[62:65], v[148:151], v[180:183], v[62:65]
	v_mfma_f32_16x16x32_bf16 v[58:61], v[156:159], v[180:183], v[58:61]
	v_mfma_f32_16x16x32_bf16 v[46:49], v[148:151], v[188:191], v[46:49]
	v_mfma_f32_16x16x32_bf16 v[42:45], v[156:159], v[188:191], v[42:45]
	v_mfma_f32_16x16x32_bf16 v[30:33], v[148:151], v[196:199], v[30:33]
	v_mfma_f32_16x16x32_bf16 v[26:29], v[156:159], v[196:199], v[26:29]
	v_mfma_f32_16x16x32_bf16 v[14:17], v[148:151], v[204:207], v[14:17]
	v_mfma_f32_16x16x32_bf16 v[10:13], v[156:159], v[204:207], v[10:13]
	v_mfma_f32_16x16x32_bf16 v[62:65], v[152:155], v[184:187], v[62:65]
	v_mfma_f32_16x16x32_bf16 v[58:61], v[160:163], v[184:187], v[58:61]
	v_mfma_f32_16x16x32_bf16 v[46:49], v[152:155], v[192:195], v[46:49]
	v_mfma_f32_16x16x32_bf16 v[42:45], v[160:163], v[192:195], v[42:45]
	v_mfma_f32_16x16x32_bf16 v[30:33], v[152:155], v[200:203], v[30:33]
	v_mfma_f32_16x16x32_bf16 v[26:29], v[160:163], v[200:203], v[26:29]
	v_mfma_f32_16x16x32_bf16 v[14:17], v[152:155], v[222:225], v[14:17]
	v_mfma_f32_16x16x32_bf16 v[10:13], v[160:163], v[222:225], v[10:13]
	v_mfma_f32_16x16x32_bf16 v[54:57], v[164:167], v[180:183], v[54:57]
	v_mfma_f32_16x16x32_bf16 v[50:53], v[172:175], v[180:183], v[50:53]
	v_mfma_f32_16x16x32_bf16 v[38:41], v[164:167], v[188:191], v[38:41]
	v_mfma_f32_16x16x32_bf16 v[34:37], v[172:175], v[188:191], v[34:37]
	v_mfma_f32_16x16x32_bf16 v[22:25], v[164:167], v[196:199], v[22:25]
	v_mfma_f32_16x16x32_bf16 v[18:21], v[172:175], v[196:199], v[18:21]
	v_mfma_f32_16x16x32_bf16 v[6:9], v[164:167], v[204:207], v[6:9]
	v_mfma_f32_16x16x32_bf16 v[2:5], v[172:175], v[204:207], v[2:5]
	v_mfma_f32_16x16x32_bf16 v[54:57], v[168:171], v[184:187], v[54:57]
	v_mfma_f32_16x16x32_bf16 v[50:53], v[176:179], v[184:187], v[50:53]
	v_mfma_f32_16x16x32_bf16 v[38:41], v[168:171], v[192:195], v[38:41]
	v_mfma_f32_16x16x32_bf16 v[34:37], v[176:179], v[192:195], v[34:37]
	v_mfma_f32_16x16x32_bf16 v[22:25], v[168:171], v[200:203], v[22:25]
	v_mfma_f32_16x16x32_bf16 v[18:21], v[176:179], v[200:203], v[18:21]
	v_mfma_f32_16x16x32_bf16 v[6:9], v[168:171], v[222:225], v[6:9]
	v_mfma_f32_16x16x32_bf16 v[2:5], v[176:179], v[222:225], v[2:5]
	s_setprio 0
	s_barrier
	s_add_i32 s73, 0, 0x18000
	v_add_u32_e32 v142, s73, v144
	s_add_i32 s61, 0, 0x1c000
	ds_read_b128 v[148:151], v142
	ds_read_b128 v[152:155], v142 offset:1024
	ds_read_b128 v[156:159], v142 offset:2048
	ds_read_b128 v[160:163], v142 offset:3072
	v_add_u32_e32 v142, s61, v144
	ds_read_b128 v[164:167], v142
	ds_read_b128 v[168:171], v142 offset:1024
	ds_read_b128 v[172:175], v142 offset:2048
	ds_read_b128 v[176:179], v142 offset:3072
	s_add_u32 s12, s26, 0x4000
	s_addc_u32 s13, s27, 0
	s_mov_b32 m0, s52
	v_lshl_add_u64 v[142:143], s[12:13], 0, v[136:137]
	ds_read_b128 v[180:183], v146 offset:32768
	ds_read_b128 v[184:187], v146 offset:33792
	ds_read_b128 v[188:191], v146 offset:34816
	ds_read_b128 v[192:195], v146 offset:35840
	ds_read_b128 v[196:199], v146 offset:36864
	ds_read_b128 v[200:203], v146 offset:37888
	ds_read_b128 v[204:207], v146 offset:38912
	ds_read_b128 v[222:225], v146 offset:39936
	global_load_lds_dwordx4 v[142:143], off
	v_lshl_add_u64 v[142:143], s[12:13], 0, v[132:133]
	s_mov_b32 m0, s53
	s_nop 0
	global_load_lds_dwordx4 v[142:143], off
	s_waitcnt vmcnt(8)
	s_waitcnt lgkmcnt(0)
	s_barrier
	s_setprio 1
	s_waitcnt lgkmcnt(0)
	v_mfma_f32_16x16x32_bf16 v[126:129], v[148:151], v[180:183], v[126:129]
	v_mfma_f32_16x16x32_bf16 v[122:125], v[156:159], v[180:183], v[122:125]
	v_mfma_f32_16x16x32_bf16 v[114:117], v[148:151], v[188:191], v[114:117]
	v_mfma_f32_16x16x32_bf16 v[106:109], v[156:159], v[188:191], v[106:109]
	v_mfma_f32_16x16x32_bf16 v[98:101], v[148:151], v[196:199], v[98:101]
	v_mfma_f32_16x16x32_bf16 v[90:93], v[156:159], v[196:199], v[90:93]
	v_mfma_f32_16x16x32_bf16 v[82:85], v[148:151], v[204:207], v[82:85]
	v_mfma_f32_16x16x32_bf16 v[74:77], v[156:159], v[204:207], v[74:77]
	v_mfma_f32_16x16x32_bf16 v[126:129], v[152:155], v[184:187], v[126:129]
	v_mfma_f32_16x16x32_bf16 v[122:125], v[160:163], v[184:187], v[122:125]
	v_mfma_f32_16x16x32_bf16 v[114:117], v[152:155], v[192:195], v[114:117]
	v_mfma_f32_16x16x32_bf16 v[106:109], v[160:163], v[192:195], v[106:109]
	v_mfma_f32_16x16x32_bf16 v[98:101], v[152:155], v[200:203], v[98:101]
	v_mfma_f32_16x16x32_bf16 v[90:93], v[160:163], v[200:203], v[90:93]
	v_mfma_f32_16x16x32_bf16 v[82:85], v[152:155], v[222:225], v[82:85]
	v_mfma_f32_16x16x32_bf16 v[74:77], v[160:163], v[222:225], v[74:77]
	v_mfma_f32_16x16x32_bf16 v[118:121], v[164:167], v[180:183], v[118:121]
	v_mfma_f32_16x16x32_bf16 v[110:113], v[172:175], v[180:183], v[110:113]
	v_mfma_f32_16x16x32_bf16 v[102:105], v[164:167], v[188:191], v[102:105]
	v_mfma_f32_16x16x32_bf16 v[94:97], v[172:175], v[188:191], v[94:97]
	v_mfma_f32_16x16x32_bf16 v[86:89], v[164:167], v[196:199], v[86:89]
	v_mfma_f32_16x16x32_bf16 v[78:81], v[172:175], v[196:199], v[78:81]
	v_mfma_f32_16x16x32_bf16 v[70:73], v[164:167], v[204:207], v[70:73]
	v_mfma_f32_16x16x32_bf16 v[66:69], v[172:175], v[204:207], v[66:69]
	v_mfma_f32_16x16x32_bf16 v[118:121], v[168:171], v[184:187], v[118:121]
	v_mfma_f32_16x16x32_bf16 v[110:113], v[176:179], v[184:187], v[110:113]
	v_mfma_f32_16x16x32_bf16 v[102:105], v[168:171], v[192:195], v[102:105]
	v_mfma_f32_16x16x32_bf16 v[94:97], v[176:179], v[192:195], v[94:97]
	v_mfma_f32_16x16x32_bf16 v[86:89], v[168:171], v[200:203], v[86:89]
	v_mfma_f32_16x16x32_bf16 v[78:81], v[176:179], v[200:203], v[78:81]
	v_mfma_f32_16x16x32_bf16 v[70:73], v[168:171], v[222:225], v[70:73]
	v_mfma_f32_16x16x32_bf16 v[66:69], v[176:179], v[222:225], v[66:69]
	s_setprio 0
	s_barrier
; #define PG8_STAGE(bufoff, gbase, voff) do { _Pragma("unroll") for (int _i = 0; _i < 2; ++_i) \
;         __builtin_amdgcn_global_load_lds((const unsigned*)((const char*)(gbase) + (voff)[_i]), (PG8_LAS unsigned*)(lds + (bufoff) + ldsw + _i * 8192), 16, 0, 0); } while (0)
; #define PG8_LDA(dst, b, h) do { _Pragma("unroll") for (int m = 0; m < 4; ++m) _Pragma("unroll") for (int k = 0; k < 2; ++k) dst[m][k] = *(const PG8_LAS bf16x8*)(lds + PG8_SA(b, h) + aoff + m * 2048 + k * 1024); } while (0)
; #define PG8_MMA(ai, bj, At, Bt) do { __builtin_amdgcn_s_setprio(1); _Pragma("unroll") for (int m = 0; m < 4; ++m) _Pragma("unroll") for (int n = 0; n < 2; ++n) _Pragma("unroll") for (int k = 0; k < 2; ++k) \
;         acc[ai][bj][m][n] = __builtin_amdgcn_mfma_f32_16x16x32_bf16(Bt[n][k], At[m][k], acc[ai][bj][m][n], 0, 0, 0); __builtin_amdgcn_s_setprio(0); } while (0)
; #define PG8_WAIT_V(n) asm volatile("s_waitcnt vmcnt(" #n ")" ::: "memory")
; #define PG8_WAIT_L(n) asm volatile("s_waitcnt lgkmcnt(" #n ")" ::: "memory")
; #define PG8_BAR __builtin_amdgcn_s_barrier()
; #define PG8_SCHED __builtin_amdgcn_sched_barrier(0)
; template <class Epi, class Sched, bool ALIGN_EPI = false, bool SP2 = false>
; __device__ __forceinline__ void gemm_phase(PG8_LAS unsigned char* lds, const Gemm g, const Sched& S, const Epi& E) {
;     ...
;             PG8_LDA(At, 1, 1); PG8_STAGE(PG8_SB(1, 0), b3, voffB); PG8_STAGE(PG8_SB(1, 1), b3 + hstepB, voffB); PG8_STAGE(PG8_SA(1, 0), a3, voffA);
;             PG8_WAIT_V(8); PG8_WAIT_L(0); PG8_BAR; PG8_MMA(1, 0, At, B0); PG8_MMA(1, 1, At, B1); PG8_BAR; PG8_SCHED;
	s_add_u32 s12, s74, s54
	s_addc_u32 s13, s75, 0
	s_add_i32 s26, s73, s23
	v_lshl_add_u64 v[142:143], s[12:13], 0, v[134:135]
	s_mov_b32 m0, s26
	ds_read_b128 v[180:183], v146 offset:49152
	ds_read_b128 v[184:187], v146 offset:50176
	ds_read_b128 v[188:191], v146 offset:51200
	ds_read_b128 v[192:195], v146 offset:52224
	ds_read_b128 v[196:199], v146 offset:53248
	ds_read_b128 v[200:203], v146 offset:54272
	ds_read_b128 v[204:207], v146 offset:55296
	ds_read_b128 v[222:225], v146 offset:56320
	global_load_lds_dwordx4 v[142:143], off
	s_add_i32 m0, s26, 0x2000
	v_lshl_add_u64 v[142:143], s[12:13], 0, v[130:131]
	s_add_u32 s12, s12, 0x4000
	s_addc_u32 s13, s13, 0
	s_add_i32 s26, s61, s23
	global_load_lds_dwordx4 v[142:143], off
	v_lshl_add_u64 v[142:143], s[12:13], 0, v[134:135]
	s_mov_b32 m0, s26
	s_nop 0
	global_load_lds_dwordx4 v[142:143], off
	v_lshl_add_u64 v[142:143], s[12:13], 0, v[130:131]
	s_add_i32 m0, s26, 0x2000
	s_nop 0
	global_load_lds_dwordx4 v[142:143], off
	v_lshl_add_u64 v[142:143], vcc, 0, v[136:137]
	s_mov_b32 m0, s55
	s_nop 0
	global_load_lds_dwordx4 v[142:143], off
	v_lshl_add_u64 v[142:143], vcc, 0, v[132:133]
	s_mov_b32 m0, s20
	s_nop 0
	global_load_lds_dwordx4 v[142:143], off
	s_waitcnt vmcnt(8)
	s_waitcnt lgkmcnt(0)
	s_barrier
	s_setprio 1
	s_waitcnt lgkmcnt(0)
	v_mfma_f32_16x16x32_bf16 v[62:65], v[148:151], v[180:183], v[62:65]
	v_mfma_f32_16x16x32_bf16 v[58:61], v[156:159], v[180:183], v[58:61]
	v_mfma_f32_16x16x32_bf16 v[46:49], v[148:151], v[188:191], v[46:49]
	v_mfma_f32_16x16x32_bf16 v[42:45], v[156:159], v[188:191], v[42:45]
	v_mfma_f32_16x16x32_bf16 v[30:33], v[148:151], v[196:199], v[30:33]
	v_mfma_f32_16x16x32_bf16 v[26:29], v[156:159], v[196:199], v[26:29]
	v_mfma_f32_16x16x32_bf16 v[14:17], v[148:151], v[204:207], v[14:17]
	v_mfma_f32_16x16x32_bf16 v[10:13], v[156:159], v[204:207], v[10:13]
	v_mfma_f32_16x16x32_bf16 v[62:65], v[152:155], v[184:187], v[62:65]
	v_mfma_f32_16x16x32_bf16 v[58:61], v[160:163], v[184:187], v[58:61]
	v_mfma_f32_16x16x32_bf16 v[46:49], v[152:155], v[192:195], v[46:49]
	v_mfma_f32_16x16x32_bf16 v[42:45], v[160:163], v[192:195], v[42:45]
	v_mfma_f32_16x16x32_bf16 v[30:33], v[152:155], v[200:203], v[30:33]
	v_mfma_f32_16x16x32_bf16 v[26:29], v[160:163], v[200:203], v[26:29]
	v_mfma_f32_16x16x32_bf16 v[14:17], v[152:155], v[222:225], v[14:17]
	v_mfma_f32_16x16x32_bf16 v[10:13], v[160:163], v[222:225], v[10:13]
	v_mfma_f32_16x16x32_bf16 v[54:57], v[164:167], v[180:183], v[54:57]
	v_mfma_f32_16x16x32_bf16 v[50:53], v[172:175], v[180:183], v[50:53]
	v_mfma_f32_16x16x32_bf16 v[38:41], v[164:167], v[188:191], v[38:41]
	v_mfma_f32_16x16x32_bf16 v[34:37], v[172:175], v[188:191], v[34:37]
	v_mfma_f32_16x16x32_bf16 v[22:25], v[164:167], v[196:199], v[22:25]
	v_mfma_f32_16x16x32_bf16 v[18:21], v[172:175], v[196:199], v[18:21]
	v_mfma_f32_16x16x32_bf16 v[6:9], v[164:167], v[204:207], v[6:9]
	v_mfma_f32_16x16x32_bf16 v[2:5], v[172:175], v[204:207], v[2:5]
	v_mfma_f32_16x16x32_bf16 v[54:57], v[168:171], v[184:187], v[54:57]
	v_mfma_f32_16x16x32_bf16 v[50:53], v[176:179], v[184:187], v[50:53]
	v_mfma_f32_16x16x32_bf16 v[38:41], v[168:171], v[192:195], v[38:41]
	v_mfma_f32_16x16x32_bf16 v[34:37], v[176:179], v[192:195], v[34:37]
	v_mfma_f32_16x16x32_bf16 v[22:25], v[168:171], v[200:203], v[22:25]
	v_mfma_f32_16x16x32_bf16 v[18:21], v[176:179], v[200:203], v[18:21]
	v_mfma_f32_16x16x32_bf16 v[6:9], v[168:171], v[222:225], v[6:9]
	v_mfma_f32_16x16x32_bf16 v[2:5], v[176:179], v[222:225], v[2:5]
	s_setprio 0
	s_barrier
	s_add_u32 s76, s76, s58
	s_addc_u32 s77, s77, 0
	s_add_u32 s6, s6, 0x400000
	s_addc_u32 s7, s7, 0
	s_cmp_ge_u32 s71, s25
	s_cbranch_scc1 .LBB0_375
